# speedup vs baseline: 1.0355x; 1.0050x over previous
; #define SBAR() __builtin_amdgcn_sched_barrier(0)
; #define SLOAD(i, k0) do { sr_[i].vs0 = *reinterpret_cast<const bf16x8*>(&Vh[(long)((k0) + sr) * LDK + sc]); sr_[i].vs1 = *reinterpret_cast<const bf16x8*>(&Vh[(long)((k0) + 32 + sr) * LDK + sc]); \
;     sr_[i].ks0 = *reinterpret_cast<const bf16x8*>(&Kh[(long)((k0) + sr) * LDK + sc]); sr_[i].ks1 = *reinterpret_cast<const bf16x8*>(&Kh[(long)((k0) + 32 + sr) * LDK + sc]); } while (0)
; DEVI void finishSM(f32x16& p0, f32x16& p1, float alpha, float& l_reg, bf16x8& pa0, bf16x8& pa1, bf16x8& pa2, bf16x8& pa3) {
; #pragma unroll
;   for (int r = 0; r < 16; ++r) p1[r] = __builtin_amdgcn_exp2f(p1[r]);
;   float ps = 0;
; #pragma unroll
;   for (int r = 0; r < 16; ++r) ps += p0[r];
; #pragma unroll
;   for (int r = 0; r < 16; ++r) ps += p1[r];
;   { auto rr = __builtin_amdgcn_permlane32_swap(__float_as_uint(ps), __float_as_uint(ps), false, false);
;     ps = __uint_as_float(rr[0]) + __uint_as_float(rr[1]); }
;   l_reg = l_reg * alpha + ps;
;     ...
;   PK4(p0, 0, pa0); PK4(p0, 8, pa1); PK4(p1, 0, pa2); PK4(p1, 8, pa3);
;     ...
; }
; DEVI void qkt(f32x16& p0, f32x16& p1, const char* Ks, const bf16x8* qr, int r32, int hi) {
;   p0 = f32x16{}; p1 = f32x16{};
; #pragma unroll
;   for (int d0 = 0; d0 < 8; ++d0) { int cb = (d0 * 16 + hi * 8) * 2;
;     bf16x8 b0 = *reinterpret_cast<const bf16x8*>(Ks + KSWZ(r32, cb));
;     bf16x8 b1 = *reinterpret_cast<const bf16x8*>(Ks + KSWZ(32 + r32, cb));
;     p0 = __builtin_amdgcn_mfma_f32_32x32x16_bf16(b0, qr[d0], p0, 0, 0, 0);
;     p1 = __builtin_amdgcn_mfma_f32_32x32x16_bf16(b1, qr[d0], p1, 0, 0, 0); }
; }
; DEVI void body(const bf16_t* __restrict__ Qb, const bf16_t* __restrict__ Kh, const bf16_t* __restrict__ Vh, bf16_t* __restrict__ Ob, int seq, char* lds) {
;     ...
;     SBAR(); qkt(pB0, pB1, K_lds + SHM_K, qr, r32, hi);
;     finishSM(pA0, pA1, alA, l_reg, pa0, pa1, pa2, pa3); SBAR();
;     SLOAD(SO, (j + 2) * KVBLK); SBAR();
;     pv_d0(o, vb0, pa0, pa1, pa2, pa3); partialSM(pB0, pB1, m_reg, mnB, alB);
.LBB0_2668:
	ds_read_b128 v[66:69], v196 offset:49152
	ds_read_b128 v[70:73], v196 offset:57344
	ds_read_b128 v[212:215], v201 offset:49152
	ds_read_b128 v[240:243], v201 offset:57344
	v_add_f32_e32 v162, 0, v163
	v_add_f32_e32 v162, v177, v162
	s_waitcnt lgkmcnt(3)
	v_mfma_f32_32x32x16_bf16 v[82:97], v[66:69], v[118:121], 0
	v_add_f32_e32 v162, v164, v162
	v_add_f32_e32 v162, v208, v162
	v_add_f32_e32 v162, v176, v162
	v_add_f32_e32 v162, v211, v162
	v_add_f32_e32 v162, v165, v162
	v_add_f32_e32 v162, v175, v162
	v_add_f32_e32 v162, v166, v162
	s_waitcnt lgkmcnt(2)
	v_mfma_f32_32x32x16_bf16 v[66:81], v[70:73], v[118:121], 0
	v_add_f32_e32 v162, v173, v162
	v_add_f32_e32 v162, v167, v162
	v_add_f32_e32 v162, v174, v162
	v_exp_f32_e32 v160, v160
	v_add_f32_e32 v162, v168, v162
	v_exp_f32_e32 v161, v161
	v_add_f32_e32 v162, v171, v162
	s_waitcnt lgkmcnt(1)
	v_mfma_f32_32x32x16_bf16 v[82:97], v[212:215], v[114:117], v[82:97]
	v_exp_f32_e32 v158, v158
	v_add_f32_e32 v162, v169, v162
	v_exp_f32_e32 v159, v159
	v_add_f32_e32 v162, v172, v162
	v_exp_f32_e32 v154, v154
	v_add_f32_e32 v162, v160, v162
	v_exp_f32_e32 v155, v155
	s_waitcnt lgkmcnt(0)
	v_mfma_f32_32x32x16_bf16 v[66:81], v[240:243], v[114:117], v[66:81]
	ds_read_b128 v[212:215], v200 offset:49152
	ds_read_b128 v[240:243], v200 offset:57344
	v_add_f32_e32 v162, v161, v162
	v_exp_f32_e32 v150, v150
	v_add_f32_e32 v162, v158, v162
	v_exp_f32_e32 v151, v151
	v_add_f32_e32 v162, v159, v162
	v_exp_f32_e32 v146, v146
	s_waitcnt lgkmcnt(1)
	v_mfma_f32_32x32x16_bf16 v[82:97], v[212:215], v[126:129], v[82:97]
	v_add_f32_e32 v162, v154, v162
	v_exp_f32_e32 v147, v147
	v_add_f32_e32 v162, v155, v162
	v_exp_f32_e32 v156, v156
	v_add_f32_e32 v162, v150, v162
	v_exp_f32_e32 v157, v157
	v_add_f32_e32 v162, v151, v162
	s_waitcnt lgkmcnt(0)
	v_mfma_f32_32x32x16_bf16 v[66:81], v[240:243], v[126:129], v[66:81]
	ds_read_b128 v[212:215], v199 offset:49152
	ds_read_b128 v[240:243], v199 offset:57344
	v_exp_f32_e32 v152, v152
	v_add_f32_e32 v162, v146, v162
	v_exp_f32_e32 v153, v153
	v_add_f32_e32 v162, v147, v162
	v_exp_f32_e32 v148, v148
	v_add_f32_e32 v162, v156, v162
	s_waitcnt lgkmcnt(1)
	v_mfma_f32_32x32x16_bf16 v[82:97], v[212:215], v[122:125], v[82:97]
	v_exp_f32_e32 v149, v149
	v_add_f32_e32 v162, v157, v162
	v_add_f32_e32 v162, v152, v162
	v_add_f32_e32 v162, v153, v162
	v_add_f32_e32 v162, v148, v162
	v_add_f32_e32 v205, v149, v162
	v_mov_b32_e32 v206, v205
	s_waitcnt lgkmcnt(0)
	v_mfma_f32_32x32x16_bf16 v[66:81], v[240:243], v[122:125], v[66:81]
	ds_read_b128 v[212:215], v198 offset:49152
	ds_read_b128 v[240:243], v198 offset:57344
	v_permlane32_swap_b32_e32 v205, v206
	s_waitcnt lgkmcnt(1)
	v_mfma_f32_32x32x16_bf16 v[82:97], v[212:215], v[110:113], v[82:97]
	s_waitcnt lgkmcnt(0)
	v_mfma_f32_32x32x16_bf16 v[66:81], v[240:243], v[110:113], v[66:81]
	ds_read_b128 v[212:215], v197 offset:49152
	ds_read_b128 v[240:243], v197 offset:57344
	s_waitcnt lgkmcnt(1)
	v_mfma_f32_32x32x16_bf16 v[82:97], v[212:215], v[106:109], v[82:97]
	s_waitcnt lgkmcnt(0)
	v_mfma_f32_32x32x16_bf16 v[66:81], v[240:243], v[106:109], v[66:81]
	ds_read_b128 v[212:215], v202 offset:49152
	ds_read_b128 v[240:243], v202 offset:57344
	s_waitcnt lgkmcnt(1)
	v_mfma_f32_32x32x16_bf16 v[82:97], v[212:215], v[102:105], v[82:97]
	s_waitcnt lgkmcnt(0)
	v_mfma_f32_32x32x16_bf16 v[66:81], v[240:243], v[102:105], v[66:81]
	ds_read_b128 v[212:215], v203 offset:49152
	ds_read_b128 v[240:243], v203 offset:57344
	v_cvt_pk_bf16_f32 v162, v163, v177
	v_cvt_pk_bf16_f32 v163, v164, v208
	v_cvt_pk_bf16_f32 v164, v176, v211
	v_cvt_pk_bf16_f32 v165, v165, v175
	v_cvt_pk_bf16_f32 v166, v166, v173
	v_cvt_pk_bf16_f32 v167, v167, v174
	s_waitcnt lgkmcnt(1)
	v_mfma_f32_32x32x16_bf16 v[82:97], v[212:215], v[98:101], v[82:97]
	v_permlane32_swap_b32_e32 v162, v164
	v_cvt_pk_bf16_f32 v168, v168, v171
	v_cvt_pk_bf16_f32 v169, v169, v172
	v_cvt_pk_bf16_f32 v172, v160, v161
	v_cvt_pk_bf16_f32 v173, v158, v159
	v_cvt_pk_bf16_f32 v174, v154, v155
	s_waitcnt lgkmcnt(0)
	v_mfma_f32_32x32x16_bf16 v[66:81], v[240:243], v[98:101], v[66:81]
	v_cvt_pk_bf16_f32 v175, v150, v151
	v_cvt_pk_bf16_f32 v208, v146, v147
	v_cvt_pk_bf16_f32 v209, v156, v157
	v_cvt_pk_bf16_f32 v210, v152, v153
	v_cvt_pk_bf16_f32 v211, v148, v149
	v_permlane32_swap_b32_e32 v163, v165
	v_permlane32_swap_b32_e32 v166, v168
	v_permlane32_swap_b32_e32 v167, v169
	v_permlane32_swap_b32_e32 v172, v174
	v_permlane32_swap_b32_e32 v173, v175
	v_permlane32_swap_b32_e32 v208, v210
	v_permlane32_swap_b32_e32 v209, v211
	s_movk_i32 s1, 0xa000
	v_add_co_u32_e32 v146, vcc, s1, v182
	s_movk_i32 s1, 0xc000
	s_nop 0
	v_addc_co_u32_e32 v147, vcc, -1, v183, vcc
	v_add_co_u32_e32 v150, vcc, s1, v182
	s_mov_b32 s1, 0xfefba000
	s_nop 0
	v_addc_co_u32_e32 v151, vcc, -1, v183, vcc
	v_add_co_u32_e32 v154, vcc, s1, v182
	s_mov_b32 s1, 0xfefbc000
	s_nop 0
	v_addc_co_u32_e32 v155, vcc, -1, v183, vcc
	v_add_co_u32_e32 v158, vcc, s1, v182
	global_load_dwordx4 v[146:149], v[146:147], off
	s_nop 0
	global_load_dwordx4 v[150:153], v[150:151], off
	v_addc_co_u32_e32 v159, vcc, -1, v183, vcc
	global_load_dwordx4 v[154:157], v[154:155], off
	s_nop 0
	global_load_dwordx4 v[158:161], v[158:159], off
	ds_read_b64_tr_b16 v[212:213], v191 offset:0
	ds_read_b64_tr_b16 v[214:215], v191 offset:0x800
	ds_read_b64_tr_b16 v[240:241], v191 offset:0x1000
	ds_read_b64_tr_b16 v[242:243], v191 offset:0x1800
	ds_read_b64_tr_b16 v[244:245], v191 offset:0x2000
	ds_read_b64_tr_b16 v[246:247], v191 offset:0x2800
	ds_read_b64_tr_b16 v[248:249], v191 offset:0x3000
	ds_read_b64_tr_b16 v[250:251], v191 offset:0x3800
	s_waitcnt lgkmcnt(6)
; #define SBAR() __builtin_amdgcn_sched_barrier(0)
; #define SWRITE(b, i) do { *(bf16x8*)(V_lds + (b) * SHM_V + vst0) = sr_[i].vs0;          \
;     *(bf16x8*)(V_lds + (b) * SHM_V + vst1) = sr_[i].vs1; int kc = sc * 2;               \
;     *(bf16x8*)(K_lds + (b) * SHM_K + KSWZ(sr, kc)) = sr_[i].ks0;                       \
;     *(bf16x8*)(K_lds + (b) * SHM_K + KSWZ(32 + sr, kc)) = sr_[i].ks1; } while (0)
; #define SWAIT() asm volatile("s_waitcnt vmcnt(4)" ::: "memory")
; #define RESC(a) do { if (__any((a) < 1.f)) { if (hi == 0) al_l[r32] = (a); asm volatile("s_waitcnt lgkmcnt(0)" ::: "memory"); \
;     for (int d = 0; d < 4; ++d) for (int r = 0; r < 16; ++r) o[d][r] *= al_l[crow(r, hi)]; } } while (0)
; template <int D0> DEVI void pv_one(f32x16& od, int vb, bf16x8 pa0, bf16x8 pa1, bf16x8 pa2, bf16x8 pa3) {
;   const s16x4 l0 = tr_read<v_rd_off(D0, 0, 0)>(vb), h0 = tr_read<v_rd_off(D0, 0, 1)>(vb), l1 = tr_read<v_rd_off(D0, 1, 0)>(vb), h1 = tr_read<v_rd_off(D0, 1, 1)>(vb);
;   const s16x4 l2 = tr_read<v_rd_off(D0, 2, 0)>(vb), h2 = tr_read<v_rd_off(D0, 2, 1)>(vb), l3 = tr_read<v_rd_off(D0, 3, 0)>(vb), h3 = tr_read<v_rd_off(D0, 3, 1)>(vb);
;   asm volatile("s_waitcnt lgkmcnt(0)" ::: "memory"); SBAR();
;     ...
;   od = __builtin_amdgcn_mfma_f32_32x32x16_bf16(pa0, PK(l0, h0), od, 0, 0, 0);
;   od = __builtin_amdgcn_mfma_f32_32x32x16_bf16(pa1, PK(l1, h1), od, 0, 0, 0);
;   od = __builtin_amdgcn_mfma_f32_32x32x16_bf16(pa2, PK(l2, h2), od, 0, 0, 0);
;   od = __builtin_amdgcn_mfma_f32_32x32x16_bf16(pa3, PK(l3, h3), od, 0, 0, 0);
;     ...
; }
; DEVI void pv_d0(f32x16* o, int vb, bf16x8 pa0, bf16x8 pa1, bf16x8 pa2, bf16x8 pa3) {
;   pv_one<0>(o[0], vb, pa0, pa1, pa2, pa3); pv_one<1>(o[1], vb, pa0, pa1, pa2, pa3); pv_one<2>(o[2], vb, pa0, pa1, pa2, pa3); pv_one<3>(o[3], vb, pa0, pa1, pa2, pa3);
; DEVI void body(const bf16_t* __restrict__ Qb, const bf16_t* __restrict__ Kh, const bf16_t* __restrict__ Vh, bf16_t* __restrict__ Ob, int seq, char* lds) {
;     ...
;     pv_d0(o, vb0, pa0, pa1, pa2, pa3); partialSM(pB0, pB1, m_reg, mnB, alB);
;     __syncthreads(); SWAIT(); SWRITE(0, SE);
;     RESC(alB); __syncthreads();
	s_nop 0
	v_mfma_f32_32x32x16_bf16 v[50:65], v[162:165], v[212:215], v[50:65]
	ds_read_b64_tr_b16 v[212:213], v191 offset:0x200
	ds_read_b64_tr_b16 v[214:215], v191 offset:0xa00
	s_waitcnt lgkmcnt(6)
	v_mfma_f32_32x32x16_bf16 v[50:65], v[166:169], v[240:243], v[50:65]
	ds_read_b64_tr_b16 v[240:241], v191 offset:0x1200
	ds_read_b64_tr_b16 v[242:243], v191 offset:0x1a00
	s_waitcnt lgkmcnt(6)
	v_mfma_f32_32x32x16_bf16 v[50:65], v[172:175], v[244:247], v[50:65]
	ds_read_b64_tr_b16 v[244:245], v191 offset:0x2200
	ds_read_b64_tr_b16 v[246:247], v191 offset:0x2a00
	s_waitcnt lgkmcnt(6)
	v_mfma_f32_32x32x16_bf16 v[50:65], v[208:211], v[248:251], v[50:65]
	ds_read_b64_tr_b16 v[248:249], v191 offset:0x3200
	ds_read_b64_tr_b16 v[250:251], v191 offset:0x3a00
	s_waitcnt lgkmcnt(6)
	v_mfma_f32_32x32x16_bf16 v[34:49], v[162:165], v[212:215], v[34:49]
	ds_read_b64_tr_b16 v[212:213], v191 offset:0x400
	ds_read_b64_tr_b16 v[214:215], v191 offset:0xc00
	s_waitcnt lgkmcnt(6)
	v_mfma_f32_32x32x16_bf16 v[34:49], v[166:169], v[240:243], v[34:49]
	ds_read_b64_tr_b16 v[240:241], v191 offset:0x1400
	ds_read_b64_tr_b16 v[242:243], v191 offset:0x1c00
	s_waitcnt lgkmcnt(6)
	v_mfma_f32_32x32x16_bf16 v[34:49], v[172:175], v[244:247], v[34:49]
	ds_read_b64_tr_b16 v[244:245], v191 offset:0x2400
	ds_read_b64_tr_b16 v[246:247], v191 offset:0x2c00
	s_waitcnt lgkmcnt(6)
	v_mfma_f32_32x32x16_bf16 v[34:49], v[208:211], v[248:251], v[34:49]
	ds_read_b64_tr_b16 v[248:249], v191 offset:0x3400
	ds_read_b64_tr_b16 v[250:251], v191 offset:0x3c00
	s_waitcnt lgkmcnt(6)
	v_mfma_f32_32x32x16_bf16 v[18:33], v[162:165], v[212:215], v[18:33]
	ds_read_b64_tr_b16 v[212:213], v191 offset:0x600
	ds_read_b64_tr_b16 v[214:215], v191 offset:0xe00
	s_waitcnt lgkmcnt(6)
	v_mfma_f32_32x32x16_bf16 v[18:33], v[166:169], v[240:243], v[18:33]
	ds_read_b64_tr_b16 v[240:241], v191 offset:0x1600
	ds_read_b64_tr_b16 v[242:243], v191 offset:0x1e00
	s_waitcnt lgkmcnt(6)
	v_mfma_f32_32x32x16_bf16 v[18:33], v[172:175], v[244:247], v[18:33]
	ds_read_b64_tr_b16 v[244:245], v191 offset:0x2600
	ds_read_b64_tr_b16 v[246:247], v191 offset:0x2e00
	s_waitcnt lgkmcnt(6)
	v_mfma_f32_32x32x16_bf16 v[18:33], v[208:211], v[248:251], v[18:33]
	ds_read_b64_tr_b16 v[248:249], v191 offset:0x3600
	ds_read_b64_tr_b16 v[250:251], v191 offset:0x3e00
	s_waitcnt lgkmcnt(6)
	v_mfma_f32_32x32x16_bf16 v[2:17], v[162:165], v[212:215], v[2:17]
	v_max_f32_e32 v162, v83, v83
	v_max_f32_e32 v163, v82, v82
	v_max_f32_e32 v162, v163, v162
	v_max3_f32 v162, v162, v84, v85
	v_max3_f32 v162, v162, v86, v87
	v_max3_f32 v162, v162, v88, v89
	v_max3_f32 v162, v162, v90, v91
	v_max3_f32 v162, v162, v92, v93
	v_max3_f32 v162, v162, v94, v95
	s_waitcnt lgkmcnt(4)
	v_mfma_f32_32x32x16_bf16 v[2:17], v[166:169], v[240:243], v[2:17]
	v_max3_f32 v162, v162, v96, v97
	v_max3_f32 v162, v162, v66, v67
	v_max3_f32 v162, v162, v68, v69
	v_max3_f32 v162, v162, v70, v71
	v_max3_f32 v162, v162, v72, v73
	v_max3_f32 v162, v162, v74, v75
	v_max3_f32 v162, v162, v76, v77
	v_max3_f32 v162, v162, v78, v79
	s_waitcnt lgkmcnt(2)
	v_mfma_f32_32x32x16_bf16 v[2:17], v[172:175], v[244:247], v[2:17]
	v_max3_f32 v162, v162, v80, v81
	v_mov_b32_e32 v163, v162
	s_nop 1
	v_permlane32_swap_b32_e32 v162, v163
	v_max_f32_e32 v163, v163, v163
	v_max_f32_e32 v162, v162, v162
	v_max_f32_e32 v162, v162, v163
	v_sub_f32_e32 v163, v162, v170
	s_mov_b32 s1, 0x42b504f3
	v_cmp_ge_f32_e32 vcc, s1, v163
	v_max_f32_e32 v163, v170, v170
	v_max_f32_e32 v162, v163, v162
	s_waitcnt lgkmcnt(0)
	v_mfma_f32_32x32x16_bf16 v[2:17], v[208:211], v[248:251], v[2:17]
	v_sub_f32_e32 v163, v170, v162
	v_mul_f32_e32 v163, 0x3e0293ee, v163
	v_exp_f32_e32 v163, v163
	s_cmp_eq_u64 vcc, exec
	s_cselect_b64 s[40:41], -1, 0
	s_barrier
	s_waitcnt vmcnt(4)
	v_cndmask_b32_e64 v207, v163, 1.0, s[40:41]
	v_cmp_gt_f32_e32 vcc, 1.0, v207
	s_waitcnt vmcnt(4)
	ds_write_b128 v193, v[134:137]
	ds_write_b128 v194, v[142:145]
	ds_write_b128 v192, v[130:133] offset:32768
	ds_write_b128 v195, v[138:141] offset:32768
	s_cbranch_vccz .LBB0_2672
	s_and_saveexec_b64 s[2:3], s[38:39]
	ds_write_b32 v188, v207 offset:128
	s_or_b64 exec, exec, s[2:3]
	s_waitcnt lgkmcnt(0)
	v_add_u32_e32 v163, v187, v0
	ds_read_b128 v[164:167], v163 offset:224
	ds_read_b128 v[172:175], v163 offset:192
	ds_read_b128 v[208:211], v163 offset:160
	ds_read_b128 v[212:215], v163 offset:128
	s_waitcnt lgkmcnt(3)
	v_pk_mul_f32 v[62:63], v[62:63], v[164:165]
	s_waitcnt lgkmcnt(2)
	v_pk_mul_f32 v[58:59], v[58:59], v[172:173]
	s_waitcnt lgkmcnt(1)
	v_pk_mul_f32 v[54:55], v[54:55], v[208:209]
	v_pk_mul_f32 v[64:65], v[64:65], v[166:167]
	v_pk_mul_f32 v[60:61], v[60:61], v[174:175]
	v_pk_mul_f32 v[56:57], v[56:57], v[210:211]
	s_waitcnt lgkmcnt(0)
	v_pk_mul_f32 v[52:53], v[52:53], v[214:215]
	v_pk_mul_f32 v[50:51], v[50:51], v[212:213]
	v_pk_mul_f32 v[46:47], v[46:47], v[164:165]
	v_pk_mul_f32 v[42:43], v[42:43], v[172:173]
	v_pk_mul_f32 v[38:39], v[38:39], v[208:209]
	v_pk_mul_f32 v[48:49], v[48:49], v[166:167]
	v_pk_mul_f32 v[44:45], v[44:45], v[174:175]
	v_pk_mul_f32 v[40:41], v[40:41], v[210:211]
	v_pk_mul_f32 v[36:37], v[36:37], v[214:215]
	v_pk_mul_f32 v[34:35], v[34:35], v[212:213]
	v_pk_mul_f32 v[30:31], v[30:31], v[164:165]
	v_pk_mul_f32 v[26:27], v[26:27], v[172:173]
	v_pk_mul_f32 v[22:23], v[22:23], v[208:209]
	v_pk_mul_f32 v[32:33], v[32:33], v[166:167]
	v_pk_mul_f32 v[28:29], v[28:29], v[174:175]
	v_pk_mul_f32 v[24:25], v[24:25], v[210:211]
	v_pk_mul_f32 v[20:21], v[20:21], v[214:215]
	v_pk_mul_f32 v[18:19], v[18:19], v[212:213]
	v_pk_mul_f32 v[14:15], v[14:15], v[164:165]
	v_pk_mul_f32 v[10:11], v[10:11], v[172:173]
	v_pk_mul_f32 v[6:7], v[6:7], v[208:209]
	v_pk_mul_f32 v[16:17], v[16:17], v[166:167]
	v_pk_mul_f32 v[12:13], v[12:13], v[174:175]
	v_pk_mul_f32 v[8:9], v[8:9], v[210:211]
	v_pk_mul_f32 v[4:5], v[4:5], v[214:215]
	v_pk_mul_f32 v[2:3], v[2:3], v[212:213]

; #define SBAR() __builtin_amdgcn_sched_barrier(0)
; #define SWRITE(b, i) do { *(bf16x8*)(V_lds + (b) * SHM_V + vst0) = sr_[i].vs0;          \
;     *(bf16x8*)(V_lds + (b) * SHM_V + vst1) = sr_[i].vs1; int kc = sc * 2;               \
;     *(bf16x8*)(K_lds + (b) * SHM_K + KSWZ(sr, kc)) = sr_[i].ks0;                       \
;     *(bf16x8*)(K_lds + (b) * SHM_K + KSWZ(32 + sr, kc)) = sr_[i].ks1; } while (0)
; #define SWAIT() asm volatile("s_waitcnt vmcnt(4)" ::: "memory")
; #define RESC(a) do { if (__any((a) < 1.f)) { if (hi == 0) al_l[r32] = (a); asm volatile("s_waitcnt lgkmcnt(0)" ::: "memory"); \
;     for (int d = 0; d < 4; ++d) for (int r = 0; r < 16; ++r) o[d][r] *= al_l[crow(r, hi)]; } } while (0)
; template <int D0> DEVI void pv_one(f32x16& od, int vb, bf16x8 pa0, bf16x8 pa1, bf16x8 pa2, bf16x8 pa3) {
;   const s16x4 l0 = tr_read<v_rd_off(D0, 0, 0)>(vb), h0 = tr_read<v_rd_off(D0, 0, 1)>(vb), l1 = tr_read<v_rd_off(D0, 1, 0)>(vb), h1 = tr_read<v_rd_off(D0, 1, 1)>(vb);
;   const s16x4 l2 = tr_read<v_rd_off(D0, 2, 0)>(vb), h2 = tr_read<v_rd_off(D0, 2, 1)>(vb), l3 = tr_read<v_rd_off(D0, 3, 0)>(vb), h3 = tr_read<v_rd_off(D0, 3, 1)>(vb);
;   asm volatile("s_waitcnt lgkmcnt(0)" ::: "memory"); SBAR();
;     ...
;   od = __builtin_amdgcn_mfma_f32_32x32x16_bf16(pa0, PK(l0, h0), od, 0, 0, 0);
;   od = __builtin_amdgcn_mfma_f32_32x32x16_bf16(pa1, PK(l1, h1), od, 0, 0, 0);
;   od = __builtin_amdgcn_mfma_f32_32x32x16_bf16(pa2, PK(l2, h2), od, 0, 0, 0);
;   od = __builtin_amdgcn_mfma_f32_32x32x16_bf16(pa3, PK(l3, h3), od, 0, 0, 0);
;     ...
; }
; DEVI void pv_d0(f32x16* o, int vb, bf16x8 pa0, bf16x8 pa1, bf16x8 pa2, bf16x8 pa3) {
;   pv_one<0>(o[0], vb, pa0, pa1, pa2, pa3); pv_one<1>(o[1], vb, pa0, pa1, pa2, pa3); pv_one<2>(o[2], vb, pa0, pa1, pa2, pa3); pv_one<3>(o[3], vb, pa0, pa1, pa2, pa3);
; DEVI void body(const bf16_t* __restrict__ Qb, const bf16_t* __restrict__ Kh, const bf16_t* __restrict__ Vh, bf16_t* __restrict__ Ob, int seq, char* lds) {
;     ...
;     pv_d0(o, vb0 + (int)SHM_V, pa0, pa1, pa2, pa3); partialSM(pA0, pA1, m_reg, mnA, alA);
;     __syncthreads(); SWAIT(); SWRITE(1, SO);
;     RESC(alA); __syncthreads();
.LBB0_2674:
	ds_read_b64_tr_b16 v[212:213], v190 offset:0
	ds_read_b64_tr_b16 v[214:215], v190 offset:0x800
	ds_read_b64_tr_b16 v[240:241], v190 offset:0x1000
	ds_read_b64_tr_b16 v[242:243], v190 offset:0x1800
	ds_read_b64_tr_b16 v[244:245], v190 offset:0x2000
	ds_read_b64_tr_b16 v[246:247], v190 offset:0x2800
	ds_read_b64_tr_b16 v[248:249], v190 offset:0x3000
	ds_read_b64_tr_b16 v[250:251], v190 offset:0x3800
	s_waitcnt lgkmcnt(6)
	s_nop 0
	v_mfma_f32_32x32x16_bf16 v[50:65], v[162:165], v[212:215], v[50:65]
	ds_read_b64_tr_b16 v[212:213], v190 offset:0x200
	ds_read_b64_tr_b16 v[214:215], v190 offset:0xa00
	s_waitcnt lgkmcnt(6)
	v_mfma_f32_32x32x16_bf16 v[50:65], v[166:169], v[240:243], v[50:65]
	ds_read_b64_tr_b16 v[240:241], v190 offset:0x1200
	ds_read_b64_tr_b16 v[242:243], v190 offset:0x1a00
	s_waitcnt lgkmcnt(6)
	v_mfma_f32_32x32x16_bf16 v[50:65], v[170:173], v[244:247], v[50:65]
	ds_read_b64_tr_b16 v[244:245], v190 offset:0x2200
	ds_read_b64_tr_b16 v[246:247], v190 offset:0x2a00
	s_waitcnt lgkmcnt(6)
	v_mfma_f32_32x32x16_bf16 v[50:65], v[174:177], v[248:251], v[50:65]
	ds_read_b64_tr_b16 v[248:249], v190 offset:0x3200
	ds_read_b64_tr_b16 v[250:251], v190 offset:0x3a00
	s_waitcnt lgkmcnt(6)
	v_mfma_f32_32x32x16_bf16 v[34:49], v[162:165], v[212:215], v[34:49]
	ds_read_b64_tr_b16 v[212:213], v190 offset:0x400
	ds_read_b64_tr_b16 v[214:215], v190 offset:0xc00
	s_waitcnt lgkmcnt(6)
	v_mfma_f32_32x32x16_bf16 v[34:49], v[166:169], v[240:243], v[34:49]
	ds_read_b64_tr_b16 v[240:241], v190 offset:0x1400
	ds_read_b64_tr_b16 v[242:243], v190 offset:0x1c00
	s_waitcnt lgkmcnt(6)
	v_mfma_f32_32x32x16_bf16 v[34:49], v[170:173], v[244:247], v[34:49]
	ds_read_b64_tr_b16 v[244:245], v190 offset:0x2400
	ds_read_b64_tr_b16 v[246:247], v190 offset:0x2c00
	s_waitcnt lgkmcnt(6)
	v_mfma_f32_32x32x16_bf16 v[34:49], v[174:177], v[248:251], v[34:49]
	ds_read_b64_tr_b16 v[248:249], v190 offset:0x3400
	ds_read_b64_tr_b16 v[250:251], v190 offset:0x3c00
	s_waitcnt lgkmcnt(6)
	v_mfma_f32_32x32x16_bf16 v[18:33], v[162:165], v[212:215], v[18:33]
	ds_read_b64_tr_b16 v[212:213], v190 offset:0x600
	ds_read_b64_tr_b16 v[214:215], v190 offset:0xe00
	s_waitcnt lgkmcnt(6)
	v_mfma_f32_32x32x16_bf16 v[18:33], v[166:169], v[240:243], v[18:33]
	ds_read_b64_tr_b16 v[240:241], v190 offset:0x1600
	ds_read_b64_tr_b16 v[242:243], v190 offset:0x1e00
	s_waitcnt lgkmcnt(6)
	v_mfma_f32_32x32x16_bf16 v[18:33], v[170:173], v[244:247], v[18:33]
	ds_read_b64_tr_b16 v[244:245], v190 offset:0x2600
	ds_read_b64_tr_b16 v[246:247], v190 offset:0x2e00
	s_waitcnt lgkmcnt(6)
	v_mfma_f32_32x32x16_bf16 v[18:33], v[174:177], v[248:251], v[18:33]
	ds_read_b64_tr_b16 v[248:249], v190 offset:0x3600
	ds_read_b64_tr_b16 v[250:251], v190 offset:0x3e00
	s_waitcnt lgkmcnt(6)
	v_mfma_f32_32x32x16_bf16 v[2:17], v[162:165], v[212:215], v[2:17]
	v_max_f32_e32 v162, v83, v83
	v_max_f32_e32 v163, v82, v82
	v_max_f32_e32 v162, v163, v162
	v_max3_f32 v162, v162, v84, v85
	v_max3_f32 v162, v162, v86, v87
	v_max3_f32 v162, v162, v88, v89
	v_max3_f32 v162, v162, v90, v91
	v_max3_f32 v162, v162, v92, v93
	v_max3_f32 v162, v162, v94, v95
	s_waitcnt lgkmcnt(4)
	v_mfma_f32_32x32x16_bf16 v[2:17], v[166:169], v[240:243], v[2:17]
	v_max3_f32 v162, v162, v96, v97
	v_max3_f32 v162, v162, v66, v67
	v_max3_f32 v162, v162, v68, v69
	v_max3_f32 v162, v162, v70, v71
	v_max3_f32 v162, v162, v72, v73
	v_max3_f32 v162, v162, v74, v75
	v_max3_f32 v162, v162, v76, v77
	v_max3_f32 v162, v162, v78, v79
	s_waitcnt lgkmcnt(2)
	v_mfma_f32_32x32x16_bf16 v[2:17], v[170:173], v[244:247], v[2:17]
	v_max3_f32 v162, v162, v80, v81
	v_mov_b32_e32 v163, v162
	s_nop 1
	v_permlane32_swap_b32_e32 v162, v163
	v_max_f32_e32 v163, v163, v163
	v_max_f32_e32 v162, v162, v162
	v_max_f32_e32 v162, v162, v163
	v_sub_f32_e32 v163, v162, v208
	v_cmp_ge_f32_e32 vcc, s1, v163
	v_max_f32_e32 v163, v208, v208
	v_max_f32_e32 v163, v163, v162
	s_waitcnt lgkmcnt(0)
	v_mfma_f32_32x32x16_bf16 v[2:17], v[174:177], v[248:251], v[2:17]
	v_sub_f32_e32 v162, v208, v163
	v_mul_f32_e32 v162, 0x3e0293ee, v162
	v_exp_f32_e32 v162, v162
	s_cmp_eq_u64 vcc, exec
	s_cselect_b64 s[40:41], -1, 0
	s_barrier
	s_waitcnt vmcnt(4)
	v_cndmask_b32_e64 v162, v162, 1.0, s[40:41]
	v_cmp_gt_f32_e32 vcc, 1.0, v162
	s_waitcnt vmcnt(3)
	ds_write_b128 v193, v[146:149] offset:16384
	s_waitcnt vmcnt(2)
	ds_write_b128 v194, v[150:153] offset:16384
	s_waitcnt vmcnt(1)
	ds_write_b128 v192, v[154:157] offset:49152
	s_waitcnt vmcnt(0)
	ds_write_b128 v195, v[158:161] offset:49152
	s_cbranch_vccz .LBB0_2678
	s_and_saveexec_b64 s[16:17], s[38:39]
	ds_write_b32 v188, v162 offset:128
	s_or_b64 exec, exec, s[16:17]
	s_waitcnt lgkmcnt(0)
	v_add_u32_e32 v158, v187, v0
	ds_read_b128 v[146:149], v158 offset:224
	ds_read_b128 v[150:153], v158 offset:192
	ds_read_b128 v[154:157], v158 offset:160
	ds_read_b128 v[158:161], v158 offset:128
	s_waitcnt lgkmcnt(3)
	v_pk_mul_f32 v[62:63], v[62:63], v[146:147]
	s_waitcnt lgkmcnt(2)
	v_pk_mul_f32 v[58:59], v[58:59], v[150:151]
	s_waitcnt lgkmcnt(1)
	v_pk_mul_f32 v[54:55], v[54:55], v[154:155]
	v_pk_mul_f32 v[64:65], v[64:65], v[148:149]
	v_pk_mul_f32 v[60:61], v[60:61], v[152:153]
	v_pk_mul_f32 v[56:57], v[56:57], v[156:157]
	s_waitcnt lgkmcnt(0)
	v_pk_mul_f32 v[52:53], v[52:53], v[160:161]
	v_pk_mul_f32 v[50:51], v[50:51], v[158:159]
	v_pk_mul_f32 v[46:47], v[46:47], v[146:147]
	v_pk_mul_f32 v[42:43], v[42:43], v[150:151]
	v_pk_mul_f32 v[38:39], v[38:39], v[154:155]
	v_pk_mul_f32 v[48:49], v[48:49], v[148:149]
	v_pk_mul_f32 v[44:45], v[44:45], v[152:153]
	v_pk_mul_f32 v[40:41], v[40:41], v[156:157]
	v_pk_mul_f32 v[36:37], v[36:37], v[160:161]
	v_pk_mul_f32 v[34:35], v[34:35], v[158:159]
	v_pk_mul_f32 v[30:31], v[30:31], v[146:147]
	v_pk_mul_f32 v[26:27], v[26:27], v[150:151]
	v_pk_mul_f32 v[22:23], v[22:23], v[154:155]
	v_pk_mul_f32 v[32:33], v[32:33], v[148:149]
	v_pk_mul_f32 v[28:29], v[28:29], v[152:153]
	v_pk_mul_f32 v[24:25], v[24:25], v[156:157]
	v_pk_mul_f32 v[20:21], v[20:21], v[160:161]
	v_pk_mul_f32 v[18:19], v[18:19], v[158:159]
	v_pk_mul_f32 v[14:15], v[14:15], v[146:147]
	v_pk_mul_f32 v[10:11], v[10:11], v[150:151]
	v_pk_mul_f32 v[6:7], v[6:7], v[154:155]
	v_pk_mul_f32 v[16:17], v[16:17], v[148:149]
	v_pk_mul_f32 v[12:13], v[12:13], v[152:153]
	v_pk_mul_f32 v[8:9], v[8:9], v[156:157]
	v_pk_mul_f32 v[4:5], v[4:5], v[160:161]
	v_pk_mul_f32 v[2:3], v[2:3], v[158:159]
